# chunk_scan loop: sign flips folded into cvt neg modifiers; global load/store addresses via SGPR base + fixed VGPR offset (no per-step 64-bit VALU address math)
# speedup vs baseline: 1.0098x; 1.0098x over previous
.LBB0_915:
	s_or_b64 exec, exec, s[12:13]
	v_lshrrev_b32_e32 v0, 4, v53
	v_and_b32_e32 v2, 15, v53
	v_bfe_u32 v55, v53, 1, 3
	v_bfe_u32 v107, v53, 4, 2
	v_lshlrev_b32_e32 v54, 7, v2
	v_bitop3_b32 v0, v0, v55, 3 bitop3:0x6c
	v_lshl_or_b32 v204, v0, 4, v54
	v_bitop3_b32 v0, v107, v55, 4 bitop3:0x36
	v_ashrrev_i32_e32 v1, 2, v53
	v_lshl_or_b32 v205, v0, 4, v54
	v_lshlrev_b32_e32 v0, 3, v107
	v_and_b32_e32 v108, -16, v1
	v_lshl_or_b32 v206, v2, 5, v0
	v_lshlrev_b32_e32 v54, 4, v2
	v_bfi_b32 v1, -16, v1, v53
	v_ashrrev_i32_e32 v53, 31, v52
	v_lshl_or_b32 v207, v107, 10, v54
	v_lshlrev_b32_e32 v208, 4, v107
	v_lshlrev_b64 v[110:111], 23, v[52:53]
	s_waitcnt lgkmcnt(0)
	s_barrier
	ds_read_b128 v[76:79], v204
	ds_read_b128 v[92:95], v204 offset:2048
	ds_read_b128 v[72:75], v205
	ds_read_b128 v[88:91], v205 offset:2048
	v_lshl_or_b32 v209, v1, 5, v0
	ds_read_b64 v[0:1], v206 offset:4096
	ds_read_b128 v[60:63], v207 offset:4608
	ds_read_b128 v[56:59], v207 offset:4864
	ds_read_b128 v[52:55], v207 offset:5120
	ds_read_b128 v[84:87], v208 offset:10816
	ds_read_b128 v[68:71], v208 offset:10880
	ds_read_b128 v[96:99], v208 offset:10752
	ds_read_b128 v[64:67], v207 offset:5376
	ds_read_b64 v[100:101], v209 offset:8704
	ds_read_b128 v[80:83], v208 offset:10944
	v_add_u32_e32 v105, v105, v106
	s_movk_i32 s12, 0x2b00
	v_mad_i64_i32 v[182:183], s[12:13], v105, s12, v[102:103]
	v_and_b32_e32 v103, 7, v104
	v_lshlrev_b32_e32 v102, 13, v107
	v_lshlrev_b32_e32 v103, 8, v103
	v_ashrrev_i32_e32 v109, 31, v108
	v_or3_b32 v110, v110, v102, v103
	v_lshl_add_u64 v[184:185], v[108:109], 2, v[110:111]
	v_mov_b32_e32 v106, 0
	v_lshl_or_b32 v184, v2, 2, v184
	s_mov_b32 s34, 0
	v_mov_b32_e32 v107, v106
	v_mov_b32_e32 v108, v106
	v_mov_b32_e32 v109, v106
	v_mov_b32_e32 v110, v106
	v_mov_b32_e32 v111, v106
	v_mov_b32_e32 v112, v106
	v_mov_b32_e32 v113, v106
	v_mov_b32_e32 v114, v106
	v_mov_b32_e32 v115, v106
	v_mov_b32_e32 v116, v106
	v_mov_b32_e32 v117, v106
	v_mov_b32_e32 v118, v106
	v_mov_b32_e32 v119, v106
	v_mov_b32_e32 v120, v106
	v_mov_b32_e32 v121, v106
	v_mov_b32_e32 v248, v182
	v_add_u32_e32 v249, 0x1000, v182
	v_add_u32_e32 v250, 0x1bf08000, v184
	s_add_u32 s100, s24, 0x4c55700
	s_addc_u32 s101, s25, 0
	s_branch .LBB0_917
.LBB0_916:
	v_cvt_pk_bf16_f32 v210, v142, v143
	v_cvt_pk_bf16_f32 v211, v144, v145
	v_cvt_pk_bf16_f32 v212, v146, v147
	v_cvt_pk_bf16_f32 v213, v148, v149
	v_cvt_pk_bf16_f32 v218, v154, v155
	v_cvt_pk_bf16_f32 v219, v156, v157
	s_nop 0
	v_lshlrev_b32_e32 v0, 16, v210
	v_and_b32_e32 v1, 0xffff0000, v210
	v_sub_f32_e32 v0, v142, v0
	v_sub_f32_e32 v1, v143, v1
	v_cvt_pk_bf16_f32 v214, v0, v1
	v_lshlrev_b32_e32 v0, 16, v211
	v_and_b32_e32 v1, 0xffff0000, v211
	v_sub_f32_e32 v0, v144, v0
	v_sub_f32_e32 v1, v145, v1
	v_mfma_f32_16x16x32_bf16 v[224:227], v[170:173], v[210:213], 0
	v_cvt_pk_bf16_f32 v215, v0, v1
	v_lshlrev_b32_e32 v0, 16, v212
	v_and_b32_e32 v1, 0xffff0000, v212
	v_sub_f32_e32 v0, v146, v0
	v_sub_f32_e32 v1, v147, v1
	v_cvt_pk_bf16_f32 v216, v0, v1
	v_lshlrev_b32_e32 v0, 16, v213
	v_and_b32_e32 v1, 0xffff0000, v213
	v_sub_f32_e32 v0, v148, v0
	v_sub_f32_e32 v1, v149, v1
	v_cvt_pk_bf16_f32 v217, v0, v1
	v_lshlrev_b32_e32 v0, 16, v218
	v_mfma_f32_16x16x32_bf16 v[170:173], v[170:173], v[214:217], v[224:227]
	v_and_b32_e32 v1, 0xffff0000, v218
	v_sub_f32_e32 v0, v154, v0
	v_sub_f32_e32 v1, v155, v1
	v_cvt_pk_bf16_f32 v222, v0, v1
	v_lshlrev_b32_e32 v0, 16, v219
	v_and_b32_e32 v1, 0xffff0000, v219
	v_cvt_pk_bf16_f32 v220, v158, v159
	v_cvt_pk_bf16_f32 v221, v160, v161
	v_sub_f32_e32 v0, v156, v0
	v_sub_f32_e32 v1, v157, v1
	v_mfma_f32_16x16x32_bf16 v[170:173], v[162:165], v[218:221], v[170:173]
	v_cvt_pk_bf16_f32 v223, v0, v1
	v_lshlrev_b32_e32 v0, 16, v220
	v_and_b32_e32 v1, 0xffff0000, v220
	v_sub_f32_e32 v0, v158, v0
	v_sub_f32_e32 v1, v159, v1
	v_cvt_pk_bf16_f32 v224, v0, v1
	v_lshlrev_b32_e32 v0, 16, v221
	v_and_b32_e32 v1, 0xffff0000, v221
	v_mov_b32_e32 v152, v3
	v_mov_b32_e32 v153, v3
	v_sub_f32_e32 v0, v160, v0
	v_sub_f32_e32 v1, v161, v1
	v_cvt_pk_bf16_f32 v225, v0, v1
	v_mov_b32_e32 v176, v3
	v_mfma_f32_16x16x32_bf16 v[162:165], v[162:165], v[222:225], v[170:173]
	v_mov_b32_e32 v177, v3
	v_pk_mul_f32 v[144:145], v[168:169], v[144:145]
	v_pk_mul_f32 v[142:143], v[166:167], v[142:143]
	v_mfma_f32_16x16x32_bf16 v[150:153], v[150:153], v[174:177], v[162:165]
	v_mfma_f32_16x16x32_bf16 v[162:165], v[118:121], v[210:213], 0
	s_nop 0
	v_mfma_f32_16x16x32_bf16 v[118:121], v[118:121], v[214:217], v[162:165]
	s_add_i32 s34, s34, 4
	v_mfma_f32_16x16x32_bf16 v[118:121], v[134:137], v[218:221], v[118:121]
	v_mfma_f32_16x16x32_bf16 v[118:121], v[134:137], v[222:225], v[118:121]
	v_mov_b32_e32 v136, v174
	v_mov_b32_e32 v137, v175
	s_nop 5
	v_cvt_pk_bf16_f32 v134, -v118, -v119
	v_cvt_pk_bf16_f32 v135, -v120, -v121
	v_lshlrev_b32_e32 v0, 16, v134
	v_and_b32_e32 v1, 0xffff0000, v134
	v_sub_f32_e64 v0, -v118, v0
	v_sub_f32_e64 v1, -v119, v1
	v_mfma_f32_16x16x32_bf16 v[142:145], v[114:117], v[134:137], v[142:145]
	v_cvt_pk_bf16_f32 v0, v0, v1
	v_lshlrev_b32_e32 v1, 16, v135
	v_and_b32_e32 v2, 0xffff0000, v135
	v_sub_f32_e64 v1, -v120, v1
	v_sub_f32_e64 v2, -v121, v2
	v_cvt_pk_bf16_f32 v1, v1, v2
	v_mov_b32_e32 v2, v3
	s_nop 1
	v_mfma_f32_16x16x32_bf16 v[118:121], v[114:117], v[0:3], v[142:145]
	v_mul_f32_e64 v116, v140, v148
	v_mul_f32_e64 v117, v141, v149
	v_pk_mul_f32 v[114:115], v[138:139], v[146:147]
	s_nop 1
	v_mfma_f32_16x16x32_bf16 v[114:117], v[110:113], v[134:137], v[114:117]
	v_mfma_f32_16x16x32_bf16 v[114:117], v[110:113], v[0:3], v[114:117]
	v_mul_f32_e64 v112, v132, v156
	v_mul_f32_e64 v113, v133, v157
	v_pk_mul_f32 v[110:111], v[130:131], v[154:155]
	s_nop 0
	v_mfma_f32_16x16x32_bf16 v[110:113], v[106:109], v[134:137], v[110:113]
	s_mov_b64 s[12:13], 0xac00
	v_mfma_f32_16x16x32_bf16 v[110:113], v[106:109], v[0:3], v[110:113]
	v_mul_f32_e64 v108, v128, v160
	v_mul_f32_e64 v109, v129, v161
	v_pk_mul_f32 v[106:107], v[126:127], v[158:159]
	v_lshl_add_u64 v[182:183], v[182:183], 0, s[12:13]
	s_mov_b64 s[12:13], 0x20000
	v_mfma_f32_16x16x32_bf16 v[106:109], v[122:125], v[134:137], v[106:109]
	v_lshl_add_u64 v[184:185], v[184:185], 0, s[12:13]
	s_andn2_b64 vcc, exec, s[40:41]
	global_store_dword v250, v150, s[24:25] offset:-4096
	v_mfma_f32_16x16x32_bf16 v[106:109], v[122:125], v[0:3], v[106:109]
	s_waitcnt lgkmcnt(9)
	v_mov_b64_e32 v[0:1], v[104:105]
	global_store_dword v250, v151, s[24:25] offset:-2048
	global_store_dword v250, v152, s[24:25]
	global_store_dword v250, v153, s[24:25] offset:2048
	v_add_u32_e32 v250, 0x8000, v250
	s_cbranch_vccz .LBB0_656
.LBB0_917:
	s_waitcnt vmcnt(7)
	ds_write_b128 v181, v[8:11] offset:11008
	s_waitcnt vmcnt(6)
	ds_write_b128 v188, v[12:15] offset:11008
	s_and_saveexec_b64 s[12:13], s[42:43]
	ds_write_b128 v189, v[16:19] offset:11008
	s_or_b64 exec, exec, s[12:13]
	s_cmpk_gt_u32 s34, 0xfa
	s_cbranch_scc1 .LBB0_923
	global_load_dwordx4 v[8:11], v248, s[100:101] offset:-4096
	s_nop 0
	global_load_dwordx4 v[12:15], v248, s[100:101]
	s_and_saveexec_b64 s[12:13], s[42:43]
	s_cbranch_execz .LBB0_922
	global_load_dwordx4 v[16:19], v249, s[100:101]
.LBB0_922:
	s_or_b64 exec, exec, s[12:13]
	s_add_u32 s100, s100, 0x2b00
	s_addc_u32 s101, s101, 0
.LBB0_923:
	v_cvt_pk_bf16_f32 v122, v118, v119
	v_cvt_pk_bf16_f32 v123, v120, v121
	v_cvt_pk_bf16_f32 v124, v114, v115
	v_cvt_pk_bf16_f32 v125, v116, v117
	v_cvt_pk_bf16_f32 v130, v110, v111
	v_cvt_pk_bf16_f32 v131, v112, v113
	s_nop 0
	v_and_b32_e32 v102, 0xffff0000, v122
	v_lshlrev_b32_e32 v2, 16, v122
	v_sub_f32_e32 v102, v119, v102
	v_sub_f32_e32 v2, v118, v2
	v_cvt_pk_bf16_f32 v126, v2, v102
	v_and_b32_e32 v102, 0xffff0000, v123
	v_lshlrev_b32_e32 v2, 16, v123
	v_sub_f32_e32 v102, v121, v102
	v_sub_f32_e32 v2, v120, v2
	v_cvt_pk_bf16_f32 v127, v2, v102
	v_and_b32_e32 v102, 0xffff0000, v124
	v_lshlrev_b32_e32 v2, 16, v124
	v_sub_f32_e32 v102, v115, v102
	v_sub_f32_e32 v2, v114, v2
	v_cvt_pk_bf16_f32 v128, v2, v102
	v_and_b32_e32 v102, 0xffff0000, v125
	v_lshlrev_b32_e32 v2, 16, v125
	v_sub_f32_e32 v102, v117, v102
	v_sub_f32_e32 v2, v116, v2
	v_cvt_pk_bf16_f32 v129, v2, v102
	v_and_b32_e32 v102, 0xffff0000, v130
	v_lshlrev_b32_e32 v2, 16, v130
	v_sub_f32_e32 v102, v111, v102
	v_sub_f32_e32 v2, v110, v2
	v_cvt_pk_bf16_f32 v146, v2, v102
	v_and_b32_e32 v102, 0xffff0000, v131
	v_lshlrev_b32_e32 v2, 16, v131
	v_sub_f32_e32 v102, v113, v102
	v_sub_f32_e32 v2, v112, v2
	v_cvt_pk_bf16_f32 v147, v2, v102
	s_waitcnt lgkmcnt(14)
	v_mfma_f32_16x16x32_bf16 v[102:105], v[92:95], v[122:125], 0
	v_cvt_pk_bf16_f32 v132, v106, v107
	v_cvt_pk_bf16_f32 v133, v108, v109
	s_waitcnt lgkmcnt(3)
	v_mov_b32_e32 v160, v100
	v_mfma_f32_16x16x32_bf16 v[92:95], v[92:95], v[126:129], v[102:105]
	v_lshlrev_b32_e32 v2, 16, v132
	v_sub_f32_e32 v2, v106, v2
	v_and_b32_e32 v134, 0xffff0000, v132
	v_mfma_f32_16x16x32_bf16 v[92:95], v[88:91], v[130:133], v[92:95]
	v_sub_f32_e32 v134, v107, v134
	v_cvt_pk_bf16_f32 v148, v2, v134
	v_lshlrev_b32_e32 v2, 16, v133
	v_sub_f32_e32 v2, v108, v2
	v_and_b32_e32 v102, 0xffff0000, v133
	v_sub_f32_e32 v102, v109, v102
	v_cvt_pk_bf16_f32 v149, v2, v102
	v_mov_b32_e32 v2, v3
	v_mfma_f32_16x16x32_bf16 v[88:91], v[88:91], v[146:149], v[92:95]
	v_mov_b32_e32 v102, v3
	v_mov_b32_e32 v103, v3
	v_mov_b32_e32 v161, v101
	v_mfma_f32_16x16x32_bf16 v[92:95], v[76:79], v[122:125], 0
	v_mul_f32_e64 v98, v120, v98
	v_mul_f32_e64 v99, v121, v99
	v_pk_mul_f32 v[96:97], v[118:119], v[96:97]
	s_waitcnt lgkmcnt(0)
	v_mfma_f32_16x16x32_bf16 v[154:157], v[0:3], v[100:103], v[88:91]
	s_barrier
	s_nop 1
	ds_read_b128 v[88:91], v204 offset:11008
	ds_read_b128 v[150:153], v204 offset:13056
	v_mfma_f32_16x16x32_bf16 v[102:105], v[76:79], v[126:129], v[92:95]
	ds_read_b128 v[142:145], v205 offset:11008
	s_nop 1
	ds_read_b128 v[92:95], v205 offset:13056
	ds_read_b64 v[76:77], v206 offset:15104
	ds_read_b128 v[138:141], v207 offset:15616
	v_mfma_f32_16x16x32_bf16 v[102:105], v[72:75], v[130:133], v[102:105]
	ds_read_b128 v[130:133], v207 offset:15872
	ds_read_b128 v[122:125], v207 offset:16128
	ds_read_b128 v[134:137], v208 offset:21824
	ds_read_b128 v[126:129], v208 offset:21888
	v_mfma_f32_16x16x32_bf16 v[72:75], v[72:75], v[146:149], v[102:105]
	s_nop 2
	ds_read_b128 v[100:103], v208 offset:21760
	ds_read_b128 v[118:121], v207 offset:16384
	s_nop 2
	v_cvt_pk_bf16_f32 v158, -v72, -v73
	v_cvt_pk_bf16_f32 v159, -v74, -v75
	v_lshlrev_b32_e32 v0, 16, v158
	v_and_b32_e32 v1, 0xffff0000, v158
	v_sub_f32_e64 v0, -v72, v0
	v_sub_f32_e64 v1, -v73, v1
	v_mfma_f32_16x16x32_bf16 v[96:99], v[60:63], v[158:161], v[96:99]
	v_cvt_pk_bf16_f32 v0, v0, v1
	v_lshlrev_b32_e32 v1, 16, v159
	v_and_b32_e32 v2, 0xffff0000, v159
	v_sub_f32_e64 v1, -v74, v1
	v_sub_f32_e64 v2, -v75, v2
	v_cvt_pk_bf16_f32 v1, v1, v2
	v_mov_b32_e32 v2, v3
	s_nop 1
	v_mfma_f32_16x16x32_bf16 v[96:99], v[60:63], v[0:3], v[96:99]
	v_mul_f32_e64 v62, v116, v86
	v_mul_f32_e64 v63, v117, v87
	v_pk_mul_f32 v[60:61], v[114:115], v[84:85]
	ds_read_b64 v[84:85], v209 offset:19712
	ds_read_b128 v[114:117], v208 offset:21952
	v_mfma_f32_16x16x32_bf16 v[60:63], v[56:59], v[158:161], v[60:63]
	v_mfma_f32_16x16x32_bf16 v[146:149], v[56:59], v[0:3], v[60:63]
	v_mul_f32_e64 v58, v112, v70
	v_mul_f32_e64 v59, v113, v71
	v_pk_mul_f32 v[56:57], v[110:111], v[68:69]
	s_nop 3
	v_mfma_f32_16x16x32_bf16 v[56:59], v[52:55], v[158:161], v[56:59]
	s_nop 0
	v_mfma_f32_16x16x32_bf16 v[110:113], v[52:55], v[0:3], v[56:59]
	v_mul_f32_e64 v54, v108, v82
	v_mul_f32_e64 v55, v109, v83
	v_pk_mul_f32 v[52:53], v[106:107], v[80:81]
	s_nop 0
	v_mfma_f32_16x16x32_bf16 v[52:55], v[64:67], v[158:161], v[52:55]
	global_store_dword v250, v154, s[24:25] offset:-4096
	v_mfma_f32_16x16x32_bf16 v[106:109], v[64:67], v[0:3], v[52:55]
	global_store_dword v250, v155, s[24:25] offset:-2048
	global_store_dword v250, v156, s[24:25]
	global_store_dword v250, v157, s[24:25] offset:2048
	v_add_u32_e32 v250, 0x8000, v250
	s_waitcnt vmcnt(9)
	ds_write_b128 v181, v[20:23]
	s_waitcnt vmcnt(8)
	ds_write_b128 v188, v[24:27]
	s_and_saveexec_b64 s[12:13], s[42:43]
	ds_write_b128 v189, v[28:31]
	s_or_b64 exec, exec, s[12:13]
	s_cmpk_gt_u32 s34, 0xf9
	s_cbranch_scc1 .LBB0_929
	global_load_dwordx4 v[20:23], v248, s[100:101] offset:-4096
	s_nop 0
	global_load_dwordx4 v[24:27], v248, s[100:101]
	s_and_saveexec_b64 s[12:13], s[42:43]
	s_cbranch_execz .LBB0_928
	global_load_dwordx4 v[28:31], v249, s[100:101]

.LBB0_929:
	v_cvt_pk_bf16_f32 v52, v96, v97
	v_cvt_pk_bf16_f32 v53, v98, v99
	v_cvt_pk_bf16_f32 v54, v146, v147
	v_cvt_pk_bf16_f32 v55, v148, v149
	v_cvt_pk_bf16_f32 v60, v110, v111
	v_cvt_pk_bf16_f32 v61, v112, v113
	s_nop 0
	v_lshlrev_b32_e32 v0, 16, v52
	v_and_b32_e32 v1, 0xffff0000, v52
	v_sub_f32_e32 v0, v96, v0
	v_sub_f32_e32 v1, v97, v1
	v_cvt_pk_bf16_f32 v56, v0, v1
	v_lshlrev_b32_e32 v0, 16, v53
	v_and_b32_e32 v1, 0xffff0000, v53
	v_sub_f32_e32 v0, v98, v0
	v_sub_f32_e32 v1, v99, v1
	s_waitcnt lgkmcnt(14)
	v_mfma_f32_16x16x32_bf16 v[66:69], v[150:153], v[52:55], 0
	v_cvt_pk_bf16_f32 v57, v0, v1
	v_lshlrev_b32_e32 v0, 16, v54
	v_and_b32_e32 v1, 0xffff0000, v54
	v_sub_f32_e32 v0, v146, v0
	v_sub_f32_e32 v1, v147, v1
	v_cvt_pk_bf16_f32 v58, v0, v1
	v_lshlrev_b32_e32 v0, 16, v55
	v_and_b32_e32 v1, 0xffff0000, v55
	v_sub_f32_e32 v0, v148, v0
	v_sub_f32_e32 v1, v149, v1
	v_cvt_pk_bf16_f32 v59, v0, v1
	v_lshlrev_b32_e32 v0, 16, v60
	v_mfma_f32_16x16x32_bf16 v[68:71], v[150:153], v[56:59], v[66:69]
	v_and_b32_e32 v1, 0xffff0000, v60
	v_sub_f32_e32 v0, v110, v0
	v_sub_f32_e32 v1, v111, v1
	v_cvt_pk_bf16_f32 v64, v0, v1
	v_lshlrev_b32_e32 v0, 16, v61
	v_and_b32_e32 v1, 0xffff0000, v61
	v_cvt_pk_bf16_f32 v62, v106, v107
	v_cvt_pk_bf16_f32 v63, v108, v109
	v_sub_f32_e32 v0, v112, v0
	v_sub_f32_e32 v1, v113, v1
	s_waitcnt lgkmcnt(12)
	v_mfma_f32_16x16x32_bf16 v[68:71], v[92:95], v[60:63], v[68:71]
	v_cvt_pk_bf16_f32 v65, v0, v1
	v_lshlrev_b32_e32 v0, 16, v62
	v_and_b32_e32 v1, 0xffff0000, v62
	v_mfma_f32_16x16x32_bf16 v[52:55], v[88:91], v[52:55], 0
	v_sub_f32_e32 v0, v106, v0
	v_sub_f32_e32 v1, v107, v1
	v_cvt_pk_bf16_f32 v66, v0, v1
	v_lshlrev_b32_e32 v0, 16, v63
	v_and_b32_e32 v1, 0xffff0000, v63
	v_mov_b32_e32 v78, v3
	v_mov_b32_e32 v79, v3
	v_sub_f32_e32 v0, v108, v0
	v_sub_f32_e32 v1, v109, v1
	v_cvt_pk_bf16_f32 v67, v0, v1
	v_mfma_f32_16x16x32_bf16 v[52:55], v[88:91], v[56:59], v[52:55]
	v_mov_b32_e32 v86, v3
	v_mov_b32_e32 v87, v3
	v_mfma_f32_16x16x32_bf16 v[68:71], v[92:95], v[64:67], v[68:71]
	s_waitcnt lgkmcnt(6)
	v_pk_mul_f32 v[112:113], v[128:129], v[112:113]
	v_pk_mul_f32 v[110:111], v[126:127], v[110:111]
	s_waitcnt lgkmcnt(2)
	v_pk_mul_f32 v[108:109], v[116:117], v[108:109]
	v_mfma_f32_16x16x32_bf16 v[156:159], v[76:79], v[84:87], v[68:71]
	v_mul_f32_e64 v106, v114, v106
	v_mul_f32_e64 v107, v115, v107
	s_waitcnt lgkmcnt(0)
	s_barrier
	v_mfma_f32_16x16x32_bf16 v[68:71], v[142:145], v[60:63], v[52:55]
	ds_read_b128 v[76:79], v204
	ds_read_b128 v[92:95], v204 offset:2048
	ds_read_b128 v[72:75], v205
	ds_read_b128 v[88:91], v205 offset:2048
	ds_read_b64 v[104:105], v206 offset:4096
	ds_read_b128 v[60:63], v207 offset:4608
	ds_read_b128 v[56:59], v207 offset:4864
	ds_read_b128 v[52:55], v207 offset:5120
	v_mfma_f32_16x16x32_bf16 v[64:67], v[142:145], v[64:67], v[68:71]
	v_mov_b32_e32 v144, v84
	v_mov_b32_e32 v145, v85
	s_nop 0
	v_pk_mul_f32 v[70:71], v[102:103], v[98:99]
	v_pk_mul_f32 v[68:69], v[100:101], v[96:97]
	s_nop 2
	v_cvt_pk_bf16_f32 v142, -v64, -v65
	v_cvt_pk_bf16_f32 v143, -v66, -v67
	v_lshlrev_b32_e32 v0, 16, v142
	v_and_b32_e32 v1, 0xffff0000, v142
	v_sub_f32_e64 v0, -v64, v0
	v_sub_f32_e64 v1, -v65, v1
	v_mfma_f32_16x16x32_bf16 v[68:71], v[138:141], v[142:145], v[68:71]
	v_cvt_pk_bf16_f32 v0, v0, v1
	v_lshlrev_b32_e32 v1, 16, v143
	v_and_b32_e32 v2, 0xffff0000, v143
	v_sub_f32_e64 v1, -v66, v1
	v_sub_f32_e64 v2, -v67, v2
	v_pk_mul_f32 v[66:67], v[136:137], v[148:149]
	v_pk_mul_f32 v[64:65], v[134:135], v[146:147]
	v_cvt_pk_bf16_f32 v1, v1, v2
	v_mov_b32_e32 v2, v3
	v_mfma_f32_16x16x32_bf16 v[134:137], v[130:133], v[142:145], v[64:67]
	s_nop 0
	v_mfma_f32_16x16x32_bf16 v[110:113], v[122:125], v[142:145], v[110:113]
	v_mfma_f32_16x16x32_bf16 v[106:109], v[118:121], v[142:145], v[106:109]
	s_nop 0
	v_mfma_f32_16x16x32_bf16 v[138:141], v[138:141], v[0:3], v[68:71]
	ds_read_b128 v[84:87], v208 offset:10816
	s_nop 1
	ds_read_b128 v[68:71], v208 offset:10880
	ds_read_b128 v[96:99], v208 offset:10752
	ds_read_b128 v[64:67], v207 offset:5376
	ds_read_b64 v[100:101], v209 offset:8704
	ds_read_b128 v[80:83], v208 offset:10944
	global_store_dword v250, v156, s[24:25] offset:-4096
	v_mfma_f32_16x16x32_bf16 v[146:149], v[130:133], v[0:3], v[134:137]
	global_store_dword v250, v157, s[24:25] offset:-2048
	global_store_dword v250, v158, s[24:25]
	global_store_dword v250, v159, s[24:25] offset:2048
	v_add_u32_e32 v250, 0x8000, v250
	s_waitcnt vmcnt(11)
	ds_write_b128 v181, v[32:35] offset:11008
	s_waitcnt vmcnt(10)
	ds_write_b128 v188, v[36:39] offset:11008
	v_mfma_f32_16x16x32_bf16 v[152:155], v[122:125], v[0:3], v[110:113]
	v_mfma_f32_16x16x32_bf16 v[158:161], v[118:121], v[0:3], v[106:109]
	s_and_saveexec_b64 s[12:13], s[42:43]
	ds_write_b128 v189, v[40:43] offset:11008
	s_or_b64 exec, exec, s[12:13]
	s_cmpk_gt_u32 s34, 0xf8
	s_cbranch_scc1 .LBB0_935
	global_load_dwordx4 v[32:35], v248, s[100:101] offset:-4096
	s_nop 0
	global_load_dwordx4 v[36:39], v248, s[100:101]
	s_and_saveexec_b64 s[12:13], s[42:43]
	s_cbranch_execz .LBB0_934
	global_load_dwordx4 v[40:43], v249, s[100:101]

.LBB0_935:
	v_cvt_pk_bf16_f32 v108, v138, v139
	v_cvt_pk_bf16_f32 v109, v140, v141
	v_cvt_pk_bf16_f32 v110, v146, v147
	v_cvt_pk_bf16_f32 v111, v148, v149
	v_cvt_pk_bf16_f32 v122, v152, v153
	v_cvt_pk_bf16_f32 v123, v154, v155
	s_nop 0
	v_lshlrev_b32_e32 v0, 16, v108
	v_and_b32_e32 v1, 0xffff0000, v108
	v_sub_f32_e32 v0, v138, v0
	v_sub_f32_e32 v1, v139, v1
	v_cvt_pk_bf16_f32 v112, v0, v1
	v_lshlrev_b32_e32 v0, 16, v109
	v_and_b32_e32 v1, 0xffff0000, v109
	v_sub_f32_e32 v0, v140, v0
	v_sub_f32_e32 v1, v141, v1
	s_waitcnt lgkmcnt(14)
	v_mfma_f32_16x16x32_bf16 v[116:119], v[92:95], v[108:111], 0
	v_cvt_pk_bf16_f32 v113, v0, v1
	v_lshlrev_b32_e32 v0, 16, v110
	v_and_b32_e32 v1, 0xffff0000, v110
	v_sub_f32_e32 v0, v146, v0
	v_sub_f32_e32 v1, v147, v1
	v_cvt_pk_bf16_f32 v114, v0, v1
	v_lshlrev_b32_e32 v0, 16, v111
	v_and_b32_e32 v1, 0xffff0000, v111
	v_sub_f32_e32 v0, v148, v0
	v_sub_f32_e32 v1, v149, v1
	v_cvt_pk_bf16_f32 v115, v0, v1
	v_lshlrev_b32_e32 v0, 16, v122
	v_mfma_f32_16x16x32_bf16 v[116:119], v[92:95], v[112:115], v[116:119]
	v_and_b32_e32 v1, 0xffff0000, v122
	v_sub_f32_e32 v0, v152, v0
	v_sub_f32_e32 v1, v153, v1
	v_cvt_pk_bf16_f32 v126, v0, v1
	v_lshlrev_b32_e32 v0, 16, v123
	v_and_b32_e32 v1, 0xffff0000, v123
	v_cvt_pk_bf16_f32 v124, v158, v159
	v_cvt_pk_bf16_f32 v125, v160, v161
	v_sub_f32_e32 v0, v154, v0
	v_sub_f32_e32 v1, v155, v1
	s_waitcnt lgkmcnt(12)
	v_mfma_f32_16x16x32_bf16 v[116:119], v[88:91], v[122:125], v[116:119]
	v_cvt_pk_bf16_f32 v127, v0, v1
	v_lshlrev_b32_e32 v0, 16, v124
	v_and_b32_e32 v1, 0xffff0000, v124
	v_sub_f32_e32 v0, v158, v0
	v_sub_f32_e32 v1, v159, v1
	v_cvt_pk_bf16_f32 v128, v0, v1
	v_lshlrev_b32_e32 v0, 16, v125
	v_and_b32_e32 v1, 0xffff0000, v125
	v_mov_b32_e32 v106, v3
	v_mov_b32_e32 v107, v3
	v_sub_f32_e32 v0, v160, v0
	v_sub_f32_e32 v1, v161, v1
	v_cvt_pk_bf16_f32 v129, v0, v1
	v_mov_b32_e32 v102, v3
	v_mfma_f32_16x16x32_bf16 v[116:119], v[88:91], v[126:129], v[116:119]
	v_mov_b32_e32 v103, v3
	s_waitcnt lgkmcnt(3)
	v_mov_b32_e32 v216, v100
	v_mov_b32_e32 v217, v101
	v_mfma_f32_16x16x32_bf16 v[210:213], v[104:107], v[100:103], v[116:119]
	v_mul_f32_e64 v154, v70, v154
	v_mul_f32_e64 v155, v71, v155
	v_pk_mul_f32 v[152:153], v[68:69], v[152:153]
	s_waitcnt lgkmcnt(2)
	v_pk_mul_f32 v[160:161], v[82:83], v[160:161]
	v_mfma_f32_16x16x32_bf16 v[106:109], v[76:79], v[108:111], 0
	v_mul_f32_e64 v158, v80, v158
	v_mul_f32_e64 v159, v81, v159
	s_waitcnt lgkmcnt(0)
	s_barrier
	v_mfma_f32_16x16x32_bf16 v[106:109], v[76:79], v[112:115], v[106:109]
	ds_read_b128 v[118:121], v204 offset:11008
	ds_read_b128 v[170:173], v204 offset:13056
	ds_read_b128 v[134:137], v205 offset:11008
	ds_read_b128 v[162:165], v205 offset:13056
	v_mfma_f32_16x16x32_bf16 v[122:125], v[72:75], v[122:125], v[106:109]
	ds_read_b64 v[150:151], v206 offset:15104
	ds_read_b128 v[114:117], v207 offset:15616
	ds_read_b128 v[110:113], v207 offset:15872
	ds_read_b128 v[106:109], v207 offset:16128
	v_mfma_f32_16x16x32_bf16 v[122:125], v[72:75], v[126:129], v[122:125]
	v_mul_f32_e64 v128, v98, v140
	v_mul_f32_e64 v129, v99, v141
	v_pk_mul_f32 v[126:127], v[96:97], v[138:139]
	ds_read_b128 v[138:141], v208 offset:21824
	ds_read_b128 v[130:133], v208 offset:21888
	s_nop 1
	v_cvt_pk_bf16_f32 v214, -v122, -v123
	v_cvt_pk_bf16_f32 v215, -v124, -v125
	v_lshlrev_b32_e32 v0, 16, v214
	v_and_b32_e32 v1, 0xffff0000, v214
	v_sub_f32_e64 v0, -v122, v0
	v_sub_f32_e64 v1, -v123, v1
	v_mfma_f32_16x16x32_bf16 v[126:129], v[60:63], v[214:217], v[126:129]
	v_cvt_pk_bf16_f32 v0, v0, v1
	v_lshlrev_b32_e32 v1, 16, v215
	v_and_b32_e32 v2, 0xffff0000, v215
	v_sub_f32_e64 v1, -v124, v1
	v_sub_f32_e64 v2, -v125, v2
	v_pk_mul_f32 v[124:125], v[86:87], v[148:149]
	v_pk_mul_f32 v[122:123], v[84:85], v[146:147]
	v_cvt_pk_bf16_f32 v1, v1, v2
	v_mov_b32_e32 v2, v3
	v_mfma_f32_16x16x32_bf16 v[152:155], v[52:55], v[214:217], v[152:155]
	s_cmpk_lt_u32 s34, 0xfc
	v_mfma_f32_16x16x32_bf16 v[146:149], v[56:59], v[214:217], v[122:125]
	s_cselect_b64 s[12:13], -1, 0
	s_cmpk_gt_u32 s34, 0xfb
	v_mfma_f32_16x16x32_bf16 v[158:161], v[64:67], v[214:217], v[158:161]
	s_cselect_b64 s[40:41], -1, 0
	s_and_b64 vcc, exec, s[40:41]
	v_mfma_f32_16x16x32_bf16 v[142:145], v[60:63], v[0:3], v[126:129]
	ds_read_b128 v[166:169], v208 offset:21760
	ds_read_b128 v[122:125], v207 offset:16384
	ds_read_b64 v[174:175], v209 offset:19712
	ds_read_b128 v[126:129], v208 offset:21952
	global_store_dword v250, v210, s[24:25] offset:-4096
	global_store_dword v250, v211, s[24:25] offset:-2048
	global_store_dword v250, v212, s[24:25]
	global_store_dword v250, v213, s[24:25] offset:2048
	v_add_u32_e32 v250, 0x8000, v250
	v_mfma_f32_16x16x32_bf16 v[146:149], v[56:59], v[0:3], v[146:149]
	v_mfma_f32_16x16x32_bf16 v[154:157], v[52:55], v[0:3], v[152:155]
	v_mfma_f32_16x16x32_bf16 v[158:161], v[64:67], v[0:3], v[158:161]
	s_cbranch_vccnz .LBB0_939
	s_waitcnt vmcnt(13)
	ds_write_b128 v181, v[44:47]
	s_waitcnt vmcnt(12)
	ds_write_b128 v188, v[48:51]
	s_and_saveexec_b64 s[50:51], s[42:43]
	ds_write_b128 v189, v[4:7]
	s_or_b64 exec, exec, s[50:51]
.LBB0_939:
	s_cmpk_gt_u32 s34, 0xf7
	s_cbranch_scc1 .LBB0_943
	s_waitcnt vmcnt(12)
	global_load_dwordx4 v[44:47], v248, s[100:101] offset:-4096
	s_nop 0
	global_load_dwordx4 v[48:51], v248, s[100:101]
	s_and_saveexec_b64 s[50:51], s[42:43]
	s_cbranch_execz .LBB0_942
	global_load_dwordx4 v[4:7], v249, s[100:101]
.LBB0_942:
	s_or_b64 exec, exec, s[50:51]
	s_add_u32 s100, s100, 0x2b00
	s_addc_u32 s101, s101, 0
